# GEMM phase prologues (7 of 11): all 14 LDS-DMA pieces issued before the first wait (vmcnt(2)->vmcnt(8)) instead of two serialized round trips; on top of attention trims
# speedup vs baseline: 1.0065x; 1.0040x over previous
; #define PG8_STAGE(bufoff, gbase, voff) do { _Pragma("unroll") for (int _i = 0; _i < 2; ++_i) \
;         __builtin_amdgcn_global_load_lds((const unsigned*)((const char*)(gbase) + (voff)[_i]), (PG8_LAS unsigned*)(lds + (bufoff) + ldsw + _i * 8192), 16, 0, 0); } while (0)
; #define PG8_WAIT_V(n) asm volatile("s_waitcnt vmcnt(" #n ")" ::: "memory")
; #define PG8_BAR __builtin_amdgcn_s_barrier()
; template <class Epi, class Sched, bool ALIGN_EPI = false, bool SP2 = false>
; __device__ __forceinline__ void gemm_phase(PG8_LAS unsigned char* lds, const Gemm g, const Sched& S, const Epi& E) {
;     ...
;     const int aoff = lds_byte(wr * 64 + fr, fq * 8), boff = lds_byte(wc * 32 + fr, fq * 8);
;     ...
;     if constexpr (SP2) {
;         PG8_STAGE(PG8_SB(0, 0), cB, voffB); PG8_STAGE(PG8_SB(0, 1), cB + hstepB, voffB); PG8_STAGE(PG8_SA(0, 0), cA, voffA); PG8_STAGE(PG8_SA(0, 1), cA + hstepA, voffA);
;         if (wr == 1) PG8_BAR;
;         PG8_WAIT_V(2); PG8_BAR;
;         PG8_STAGE(PG8_SB(1, 0), cB + kstep, voffB); PG8_STAGE(PG8_SA(1, 0), cA + kstep, voffA); PG8_STAGE(PG8_SB(1, 1), cB + hstepB + kstep, voffB);
;         PG8_WAIT_V(6); PG8_BAR;
.LBB0_305:
	s_add_u32 s40, s26, 0x10800000
	s_addc_u32 s41, s27, 0
	s_add_u32 s42, s26, 0x14820000
	s_mov_b64 s[46:47], 0x80
	s_addc_u32 s43, s27, 0
	s_lshl_b32 s5, s5, 5
	s_add_i32 m0, s9, 0x18000
	v_lshl_add_u64 v[6:7], v[6:7], 0, s[46:47]
	s_lshl_b32 s33, s4, 13
	s_and_b32 s31, s5, 0x60
	global_load_lds_dwordx4 v[6:7], off
	v_lshl_add_u64 v[4:5], v[4:5], 0, s[46:47]
	s_add_i32 m0, s9, 0x1a000
	s_add_i32 s34, s9, 0x8000
	s_add_i32 s35, s9, 0xa000
	global_load_lds_dwordx4 v[4:5], off
	v_lshl_add_u64 v[0:1], v[0:1], 0, s[46:47]
	s_mov_b32 m0, s34
	s_add_u32 s48, s68, 0x80080
	global_load_lds_dwordx4 v[0:1], off
	v_lshl_add_u64 v[0:1], v[2:3], 0, s[46:47]
	s_mov_b32 m0, s35
	s_addc_u32 s49, s69, 0
	global_load_lds_dwordx4 v[0:1], off
	s_add_i32 m0, s9, 0x1c000
	v_lshl_add_u64 v[0:1], s[48:49], 0, v[130:131]
	global_load_lds_dwordx4 v[0:1], off
	v_lshl_add_u64 v[0:1], s[48:49], 0, v[134:135]
	s_add_i32 m0, s9, 0x1e000
	v_lshlrev_b32_e32 v2, 12, v169
	global_load_lds_dwordx4 v[0:1], off
	s_waitcnt vmcnt(8)
	s_barrier
	v_lshlrev_b32_e32 v1, 2, v171
	v_lshl_or_b32 v0, v171, 6, v172
	v_and_b32_e32 v1, 32, v1
	v_bitop3_b32 v0, v0, s33, v1 bitop3:0xde
	v_lshlrev_b32_e32 v1, 9, v162
	v_and_b32_e32 v1, 0x70000, v1
	v_or3_b32 v1, v163, v1, v2
	v_add_u32_e32 v140, v1, v168
	v_lshlrev_b32_e32 v1, 5, v170
	s_waitcnt vmcnt(6)
	s_cmpk_lt_u32 s20, 0x100
	v_and_b32_e32 v1, 0xf0000, v1
	v_lshl_or_b32 v174, s31, 7, v173
	s_cselect_b64 s[48:49], -1, 0
	v_or3_b32 v1, v163, v1, v2
	s_add_i32 s72, 0, 0x10000
	s_add_i32 s73, 0, 0x14000
	s_mov_b32 s50, 0xffa00000
	v_lshl_or_b32 v137, s4, 6, v171
	v_or_b32_e32 v175, s31, v136
	v_mov_b32_e32 v141, v139
	v_add_u32_e32 v142, v1, v168
	v_mov_b32_e32 v143, v139
	v_mov_b64_e32 v[144:145], 0x1290
	v_mov_b64_e32 v[146:147], 0x128f
	v_add_u32_e32 v176, s72, v174
	v_add_u32_e32 v177, s73, v174
	v_add_u32_e32 v178, 0, v0
	s_mov_b32 s51, -1
	s_movk_i32 s74, 0x4800
	s_mov_b32 s75, 0
	s_barrier
	s_branch .LBB0_308

; #define PG8_STAGE(bufoff, gbase, voff) do { _Pragma("unroll") for (int _i = 0; _i < 2; ++_i) \
;         __builtin_amdgcn_global_load_lds((const unsigned*)((const char*)(gbase) + (voff)[_i]), (PG8_LAS unsigned*)(lds + (bufoff) + ldsw + _i * 8192), 16, 0, 0); } while (0)
; #define PG8_WAIT_V(n) asm volatile("s_waitcnt vmcnt(" #n ")" ::: "memory")
; #define PG8_BAR __builtin_amdgcn_s_barrier()
; template <class Epi, class Sched, bool ALIGN_EPI = false, bool SP2 = false>
; __device__ __forceinline__ void gemm_phase(PG8_LAS unsigned char* lds, const Gemm g, const Sched& S, const Epi& E) {
;     ...
;     const int aoff = lds_byte(wr * 64 + fr, fq * 8), boff = lds_byte(wc * 32 + fr, fq * 8);
;     ...
;     if constexpr (SP2) {
;         PG8_STAGE(PG8_SB(0, 0), cB, voffB); PG8_STAGE(PG8_SB(0, 1), cB + hstepB, voffB); PG8_STAGE(PG8_SA(0, 0), cA, voffA); PG8_STAGE(PG8_SA(0, 1), cA + hstepA, voffA);
;         if (wr == 1) PG8_BAR;
;         PG8_WAIT_V(2); PG8_BAR;
;         PG8_STAGE(PG8_SB(1, 0), cB + kstep, voffB); PG8_STAGE(PG8_SA(1, 0), cA + kstep, voffA); PG8_STAGE(PG8_SB(1, 1), cB + hstepB + kstep, voffB);
;         PG8_WAIT_V(6); PG8_BAR;
.LBB0_491:
	s_add_u32 s76, s26, 0x12800000
	s_addc_u32 s77, s27, 0
	s_add_u32 s18, s26, 0x14c20000
	s_mov_b64 s[20:21], 0x80
	s_addc_u32 s19, s27, 0
	s_lshl_b32 s5, s5, 5
	s_add_i32 m0, s69, 0x18000
	v_lshl_add_u64 v[6:7], v[6:7], 0, s[20:21]
	s_lshl_b32 s7, s4, 13
	s_and_b32 s5, s5, 0x60
	global_load_lds_dwordx4 v[6:7], off
	v_lshl_add_u64 v[4:5], v[4:5], 0, s[20:21]
	s_add_i32 m0, s69, 0x1a000
	s_add_i32 s78, s69, 0x8000
	s_add_i32 s79, s69, 0xa000
	global_load_lds_dwordx4 v[4:5], off
	v_lshl_add_u64 v[2:3], v[2:3], 0, s[20:21]
	s_mov_b32 m0, s78
	s_add_u32 s28, s60, 0x80080
	global_load_lds_dwordx4 v[2:3], off
	v_lshl_add_u64 v[0:1], v[0:1], 0, s[20:21]
	s_mov_b32 m0, s79
	s_addc_u32 s29, s61, 0
	global_load_lds_dwordx4 v[0:1], off
	s_add_i32 m0, s69, 0x1c000
	v_lshl_add_u64 v[0:1], s[28:29], 0, v[130:131]
	global_load_lds_dwordx4 v[0:1], off
	v_lshl_add_u64 v[0:1], s[28:29], 0, v[134:135]
	s_add_i32 m0, s69, 0x1e000
	v_lshlrev_b32_e32 v2, 12, v169
	global_load_lds_dwordx4 v[0:1], off
	s_waitcnt vmcnt(8)
	s_barrier
	v_lshlrev_b32_e32 v1, 2, v171
	v_lshl_or_b32 v0, v171, 6, v172
	v_and_b32_e32 v1, 32, v1
	v_bitop3_b32 v0, v0, s7, v1 bitop3:0xde
	v_lshlrev_b32_e32 v1, 9, v162
	v_and_b32_e32 v1, 0x70000, v1
	v_or3_b32 v1, v163, v1, v2
	v_add_u32_e32 v138, v1, v168
	v_lshlrev_b32_e32 v1, 5, v170
	s_waitcnt vmcnt(6)
	s_cmpk_lt_u32 s22, 0x100
	v_and_b32_e32 v1, 0xf0000, v1
	v_lshl_or_b32 v153, s5, 7, v173
	s_cselect_b64 s[22:23], -1, 0
	v_or3_b32 v1, v163, v1, v2
	s_add_i32 s81, 0, 0x10000
	s_add_i32 s82, 0, 0x14000
	v_lshl_or_b32 v152, s4, 6, v171
	s_ashr_i32 s80, s35, 31
	v_or_b32_e32 v154, s5, v136
	v_mov_b32_e32 v139, v137
	v_add_u32_e32 v140, v1, v168
	v_mov_b32_e32 v141, v137
	v_mov_b64_e32 v[142:143], 0x210
	v_mov_b64_e32 v[144:145], 0x20f
	v_add_u32_e32 v155, s81, v153
	v_add_u32_e32 v156, s82, v153
	v_add_u32_e32 v157, 0, v0
	s_mov_b32 s83, 0x10800
	s_barrier
	s_branch .LBB0_494

; #define PG8_STAGE(bufoff, gbase, voff) do { _Pragma("unroll") for (int _i = 0; _i < 2; ++_i) \
;         __builtin_amdgcn_global_load_lds((const unsigned*)((const char*)(gbase) + (voff)[_i]), (PG8_LAS unsigned*)(lds + (bufoff) + ldsw + _i * 8192), 16, 0, 0); } while (0)
; #define PG8_WAIT_V(n) asm volatile("s_waitcnt vmcnt(" #n ")" ::: "memory")
; #define PG8_BAR __builtin_amdgcn_s_barrier()
; template <class Epi, class Sched, bool ALIGN_EPI = false, bool SP2 = false>
; __device__ __forceinline__ void gemm_phase(PG8_LAS unsigned char* lds, const Gemm g, const Sched& S, const Epi& E) {
;     ...
;     const int aoff = lds_byte(wr * 64 + fr, fq * 8), boff = lds_byte(wc * 32 + fr, fq * 8);
;     ...
;     if constexpr (SP2) {
;         PG8_STAGE(PG8_SB(0, 0), cB, voffB); PG8_STAGE(PG8_SB(0, 1), cB + hstepB, voffB); PG8_STAGE(PG8_SA(0, 0), cA, voffA); PG8_STAGE(PG8_SA(0, 1), cA + hstepA, voffA);
;         if (wr == 1) PG8_BAR;
;         PG8_WAIT_V(2); PG8_BAR;
;         PG8_STAGE(PG8_SB(1, 0), cB + kstep, voffB); PG8_STAGE(PG8_SA(1, 0), cA + kstep, voffA); PG8_STAGE(PG8_SB(1, 1), cB + hstepB + kstep, voffB);
;         PG8_WAIT_V(6); PG8_BAR;
.LBB0_821:
	v_readlane_b32 s8, v240, 3
	v_readlane_b32 s9, v240, 4
	v_readlane_b32 s10, v240, 5
	v_readlane_b32 s11, v240, 6
	s_add_u32 s8, s8, 0x15803800
	s_addc_u32 s9, s9, 0
	s_lshl_b32 s5, s5, 5
	s_mov_b64 s[10:11], 0x80
	s_and_b32 s5, s5, 0x60
	s_add_i32 m0, s33, 0x18000
	v_lshl_add_u64 v[6:7], v[6:7], 0, s[10:11]
	s_lshl_b32 s18, s4, 13
	s_lshl_b32 s19, s5, 7
	global_load_lds_dwordx4 v[6:7], off
	v_lshl_add_u64 v[4:5], v[4:5], 0, s[10:11]
	s_add_i32 m0, s33, 0x1a000
	s_add_i32 s47, s33, 0x8000
	s_add_i32 s48, s33, 0xa000
	global_load_lds_dwordx4 v[4:5], off
	v_lshl_add_u64 v[0:1], v[0:1], 0, s[10:11]
	s_mov_b32 m0, s47
	s_add_u32 s16, s40, 0x40080
	global_load_lds_dwordx4 v[0:1], off
	v_lshl_add_u64 v[0:1], v[2:3], 0, s[10:11]
	s_mov_b32 m0, s48
	s_addc_u32 s17, s41, 0
	global_load_lds_dwordx4 v[0:1], off
	s_add_i32 m0, s33, 0x1c000
	v_lshl_add_u64 v[0:1], s[16:17], 0, v[132:133]
	global_load_lds_dwordx4 v[0:1], off
	v_lshl_add_u64 v[0:1], s[16:17], 0, v[128:129]
	s_add_i32 m0, s33, 0x1e000
	s_sext_i32_i8 s54, s0
	global_load_lds_dwordx4 v[0:1], off
	s_waitcnt vmcnt(8)
	s_barrier
	v_and_b32_e32 v0, 15, v162
	v_lshlrev_b32_e32 v1, 1, v8
	v_lshlrev_b32_e32 v2, 2, v162
	v_lshlrev_b32_e32 v3, 6, v162
	s_movk_i32 s0, 0x3c0
	v_lshl_or_b32 v150, s4, 6, v0
	v_lshl_or_b32 v0, v0, 6, v1
	v_and_b32_e32 v2, 32, v2
	v_and_or_b32 v1, v3, s0, v1
	s_waitcnt vmcnt(6)
	s_cmpk_lt_u32 s1, 0x100
	v_bitop3_b32 v0, v0, s18, v2 bitop3:0xde
	v_bitop3_b32 v151, s19, v1, v2 bitop3:0xf6
	s_cselect_b64 s[16:17], -1, 0
	s_add_i32 s49, 0, 0x10000
	s_add_i32 s50, 0, 0x14000
	v_or_b32_e32 v152, s5, v8
	v_add3_u32 v136, v12, v9, v10
	v_mov_b32_e32 v137, v133
	v_add3_u32 v138, v11, v9, v10
	v_mov_b32_e32 v139, v133
	v_mov_b64_e32 v[140:141], 0x420
	v_mov_b64_e32 v[142:143], 0x41f
	v_add_u32_e32 v153, s49, v151
	v_add_u32_e32 v154, s50, v151
	v_add_u32_e32 v155, 0, v0
	s_mov_b32 s51, 0xc1f00000
	v_mov_b32_e32 v156, 0x41f00000
	s_barrier
	s_branch .LBB0_824

; #define PG8_STAGE(bufoff, gbase, voff) do { _Pragma("unroll") for (int _i = 0; _i < 2; ++_i) \
;         __builtin_amdgcn_global_load_lds((const unsigned*)((const char*)(gbase) + (voff)[_i]), (PG8_LAS unsigned*)(lds + (bufoff) + ldsw + _i * 8192), 16, 0, 0); } while (0)
; #define PG8_WAIT_V(n) asm volatile("s_waitcnt vmcnt(" #n ")" ::: "memory")
; #define PG8_BAR __builtin_amdgcn_s_barrier()
; template <class Epi, class Sched, bool ALIGN_EPI = false, bool SP2 = false>
; __device__ __forceinline__ void gemm_phase(PG8_LAS unsigned char* lds, const Gemm g, const Sched& S, const Epi& E) {
;     ...
;     const int aoff = lds_byte(wr * 64 + fr, fq * 8), boff = lds_byte(wc * 32 + fr, fq * 8);
;     ...
;     if constexpr (SP2) {
;         PG8_STAGE(PG8_SB(0, 0), cB, voffB); PG8_STAGE(PG8_SB(0, 1), cB + hstepB, voffB); PG8_STAGE(PG8_SA(0, 0), cA, voffA); PG8_STAGE(PG8_SA(0, 1), cA + hstepA, voffA);
;         if (wr == 1) PG8_BAR;
;         PG8_WAIT_V(2); PG8_BAR;
;         PG8_STAGE(PG8_SB(1, 0), cB + kstep, voffB); PG8_STAGE(PG8_SA(1, 0), cA + kstep, voffA); PG8_STAGE(PG8_SB(1, 1), cB + hstepB + kstep, voffB);
;         PG8_WAIT_V(6); PG8_BAR;
.LBB0_917:
	s_lshl_b32 s16, s16, 5
	s_and_b32 s22, s16, 0x60
	s_mov_b64 s[16:17], 0x80
	s_add_i32 m0, s29, 0x18000
	v_lshl_add_u64 v[6:7], v[6:7], 0, s[16:17]
	s_lshl_b32 s19, s18, 13
	global_load_lds_dwordx4 v[6:7], off
	v_lshl_add_u64 v[2:3], v[2:3], 0, s[16:17]
	s_add_i32 m0, s29, 0x1a000
	s_add_i32 s35, s29, 0x8000
	s_add_i32 s51, s29, 0xa000
	global_load_lds_dwordx4 v[2:3], off
	v_lshl_add_u64 v[0:1], v[0:1], 0, s[16:17]
	s_mov_b32 m0, s35
	s_add_u32 s20, s54, 0x80080
	global_load_lds_dwordx4 v[0:1], off
	v_lshl_add_u64 v[0:1], v[4:5], 0, s[16:17]
	s_mov_b32 m0, s51
	s_addc_u32 s21, s55, 0
	global_load_lds_dwordx4 v[0:1], off
	s_add_i32 m0, s29, 0x1c000
	v_lshl_add_u64 v[0:1], s[20:21], 0, v[130:131]
	global_load_lds_dwordx4 v[0:1], off
	v_lshl_add_u64 v[0:1], s[20:21], 0, v[134:135]
	s_add_i32 m0, s29, 0x1e000
	v_lshlrev_b32_e32 v2, 12, v10
	global_load_lds_dwordx4 v[0:1], off
	s_waitcnt vmcnt(8)
	s_barrier
	v_lshlrev_b32_e32 v1, 2, v146
	v_lshl_or_b32 v0, v146, 6, v148
	v_and_b32_e32 v1, 32, v1
	v_bitop3_b32 v0, v0, s19, v1 bitop3:0xde
	v_lshlrev_b32_e32 v1, 9, v162
	v_and_b32_e32 v1, 0x70000, v1
	v_or3_b32 v1, v8, v1, v2
	v_add_u32_e32 v136, v1, v9
	v_lshlrev_b32_e32 v1, 5, v11
	s_waitcnt vmcnt(6)
	s_cmpk_lt_u32 s5, 0x100
	v_and_b32_e32 v1, 0xf0000, v1
	v_lshl_or_b32 v150, s18, 6, v146
	v_lshl_or_b32 v151, s22, 7, v149
	s_cselect_b64 s[18:19], -1, 0
	v_or3_b32 v1, v8, v1, v2
	s_add_i32 s58, 0, 0x10000
	s_add_i32 s59, 0, 0x14000
	s_sext_i32_i8 s64, s4
	v_or_b32_e32 v152, s22, v147
	v_mov_b32_e32 v137, v131
	v_add_u32_e32 v138, v1, v9
	v_mov_b32_e32 v139, v131
	v_mov_b64_e32 v[140:141], 0x400
	v_mov_b64_e32 v[142:143], 0x3ff
	v_add_u32_e32 v153, s58, v151
	v_add_u32_e32 v154, s59, v151
	v_add_u32_e32 v155, 0, v0
	s_mov_b32 s60, 0x80000
	s_mov_b64 s[20:21], 0x90000
	s_mov_b32 s61, 0x90000
	s_mov_b64 s[22:23], 0xa0000
	s_mov_b32 s62, 0xa0000
	s_mov_b64 s[40:41], 0xb0000
	s_mov_b32 s63, 0xb0000
	s_barrier
	s_branch .LBB0_920

; #define PG8_STAGE(bufoff, gbase, voff) do { _Pragma("unroll") for (int _i = 0; _i < 2; ++_i) \
;         __builtin_amdgcn_global_load_lds((const unsigned*)((const char*)(gbase) + (voff)[_i]), (PG8_LAS unsigned*)(lds + (bufoff) + ldsw + _i * 8192), 16, 0, 0); } while (0)
; #define PG8_WAIT_V(n) asm volatile("s_waitcnt vmcnt(" #n ")" ::: "memory")
; #define PG8_BAR __builtin_amdgcn_s_barrier()
; template <class Epi, class Sched, bool ALIGN_EPI = false, bool SP2 = false>
; __device__ __forceinline__ void gemm_phase(PG8_LAS unsigned char* lds, const Gemm g, const Sched& S, const Epi& E) {
;     ...
;     const int aoff = lds_byte(wr * 64 + fr, fq * 8), boff = lds_byte(wc * 32 + fr, fq * 8);
;     ...
;     if constexpr (SP2) {
;         PG8_STAGE(PG8_SB(0, 0), cB, voffB); PG8_STAGE(PG8_SB(0, 1), cB + hstepB, voffB); PG8_STAGE(PG8_SA(0, 0), cA, voffA); PG8_STAGE(PG8_SA(0, 1), cA + hstepA, voffA);
;         if (wr == 1) PG8_BAR;
;         PG8_WAIT_V(2); PG8_BAR;
;         PG8_STAGE(PG8_SB(1, 0), cB + kstep, voffB); PG8_STAGE(PG8_SA(1, 0), cA + kstep, voffA); PG8_STAGE(PG8_SB(1, 1), cB + hstepB + kstep, voffB);
;         PG8_WAIT_V(6); PG8_BAR;
.LBB0_937:
	s_mov_b64 s[16:17], 0x80
	s_lshl_b32 s4, s4, 5
	s_add_i32 m0, s21, 0x18000
	v_lshl_add_u64 v[6:7], v[6:7], 0, s[16:17]
	s_lshl_b32 s19, s1, 13
	s_and_b32 s44, s4, 0x60
	global_load_lds_dwordx4 v[6:7], off
	v_lshl_add_u64 v[4:5], v[4:5], 0, s[16:17]
	s_add_i32 m0, s21, 0x1a000
	s_add_i32 s35, s21, 0x8000
	s_add_i32 s70, s21, 0xa000
	global_load_lds_dwordx4 v[4:5], off
	v_lshl_add_u64 v[0:1], v[0:1], 0, s[16:17]
	s_mov_b32 m0, s35
	s_add_u32 s4, s42, 0x80080
	global_load_lds_dwordx4 v[0:1], off
	v_lshl_add_u64 v[0:1], v[2:3], 0, s[16:17]
	s_mov_b32 m0, s70
	s_addc_u32 s5, s43, 0
	global_load_lds_dwordx4 v[0:1], off
	s_add_i32 m0, s21, 0x1c000
	v_lshl_add_u64 v[0:1], s[4:5], 0, v[130:131]
	global_load_lds_dwordx4 v[0:1], off
	v_lshl_add_u64 v[0:1], s[4:5], 0, v[134:135]
	s_add_i32 m0, s21, 0x1e000
	s_cmpk_lt_u32 s0, 0x100
	global_load_lds_dwordx4 v[0:1], off
	s_waitcnt vmcnt(8)
	s_barrier
	v_lshlrev_b32_e32 v1, 2, v146
	v_lshl_or_b32 v0, v146, 6, v148
	v_and_b32_e32 v1, 32, v1
	v_lshl_or_b32 v141, s44, 7, v149
	s_waitcnt vmcnt(6)
	s_cselect_b64 s[40:41], -1, 0
	s_add_i32 s74, 0, 0x10000
	v_bitop3_b32 v0, v0, s19, v1 bitop3:0xde
	s_add_i32 s71, 0, 0x14000
	v_add_u32_e32 v143, s74, v141
	s_add_i32 s74, s74, s30
	v_lshl_or_b32 v140, s1, 6, v146
	v_or_b32_e32 v142, s44, v147
	v_mov_b64_e32 v[136:137], 0x100
	v_mov_b64_e32 v[138:139], 0xff
	v_add_u32_e32 v144, s71, v141
	v_add_u32_e32 v145, 0, v0
	s_add_i32 s72, s21, 0xc000
	s_add_i32 s73, s21, 0xe000
	s_add_i32 s75, s74, 0x2000
	s_barrier
	s_branch .LBB0_940

; #define PG8_STAGE(bufoff, gbase, voff) do { _Pragma("unroll") for (int _i = 0; _i < 2; ++_i) \
;         __builtin_amdgcn_global_load_lds((const unsigned*)((const char*)(gbase) + (voff)[_i]), (PG8_LAS unsigned*)(lds + (bufoff) + ldsw + _i * 8192), 16, 0, 0); } while (0)
; #define PG8_WAIT_V(n) asm volatile("s_waitcnt vmcnt(" #n ")" ::: "memory")
; #define PG8_BAR __builtin_amdgcn_s_barrier()
; template <class Epi, class Sched, bool ALIGN_EPI = false, bool SP2 = false>
; __device__ __forceinline__ void gemm_phase(PG8_LAS unsigned char* lds, const Gemm g, const Sched& S, const Epi& E) {
;     ...
;     const int aoff = lds_byte(wr * 64 + fr, fq * 8), boff = lds_byte(wc * 32 + fr, fq * 8);
;     ...
;     if constexpr (SP2) {
;         PG8_STAGE(PG8_SB(0, 0), cB, voffB); PG8_STAGE(PG8_SB(0, 1), cB + hstepB, voffB); PG8_STAGE(PG8_SA(0, 0), cA, voffA); PG8_STAGE(PG8_SA(0, 1), cA + hstepA, voffA);
;         if (wr == 1) PG8_BAR;
;         PG8_WAIT_V(2); PG8_BAR;
;         PG8_STAGE(PG8_SB(1, 0), cB + kstep, voffB); PG8_STAGE(PG8_SA(1, 0), cA + kstep, voffA); PG8_STAGE(PG8_SB(1, 1), cB + hstepB + kstep, voffB);
;         PG8_WAIT_V(6); PG8_BAR;
.LBB0_1151:
	s_lshl_b32 s10, s10, 5
	s_and_b32 s20, s10, 0x60
	s_mov_b64 s[10:11], 0x80
	s_add_i32 m0, s29, 0x18000
	v_lshl_add_u64 v[6:7], v[6:7], 0, s[10:11]
	s_lshl_b32 s17, s16, 13
	global_load_lds_dwordx4 v[6:7], off
	v_lshl_add_u64 v[4:5], v[4:5], 0, s[10:11]
	s_add_i32 m0, s29, 0x1a000
	s_add_i32 s35, s29, 0x8000
	s_add_i32 s47, s29, 0xa000
	global_load_lds_dwordx4 v[4:5], off
	v_lshl_add_u64 v[0:1], v[0:1], 0, s[10:11]
	s_mov_b32 m0, s35
	s_add_u32 s18, s50, 0x200080
	global_load_lds_dwordx4 v[0:1], off
	v_lshl_add_u64 v[0:1], v[2:3], 0, s[10:11]
	s_mov_b32 m0, s47
	s_addc_u32 s19, s51, 0
	global_load_lds_dwordx4 v[0:1], off
	s_add_i32 m0, s29, 0x1c000
	v_lshl_add_u64 v[0:1], s[18:19], 0, v[130:131]
	global_load_lds_dwordx4 v[0:1], off
	v_lshl_add_u64 v[0:1], s[18:19], 0, v[134:135]
	s_add_i32 m0, s29, 0x1e000
	v_lshlrev_b32_e32 v2, 14, v148
	global_load_lds_dwordx4 v[0:1], off
	s_waitcnt vmcnt(8)
	s_barrier
	v_lshlrev_b32_e32 v1, 2, v149
	v_lshl_or_b32 v0, v149, 6, v152
	v_and_b32_e32 v1, 32, v1
	v_bitop3_b32 v0, v0, s17, v1 bitop3:0xde
	v_lshlrev_b32_e32 v1, 11, v162
	v_and_b32_e32 v1, 0x1c0000, v1
	v_or3_b32 v1, v146, v1, v2
	v_add_u32_e32 v136, v1, v147
	v_lshlrev_b32_e32 v1, 7, v151
	s_waitcnt vmcnt(6)
	s_cmpk_lt_u32 s5, 0x100
	v_and_b32_e32 v1, 0x3c0000, v1
	v_lshl_or_b32 v154, s16, 6, v149
	v_lshl_or_b32 v155, s20, 7, v153
	s_cselect_b64 s[16:17], -1, 0
	v_or3_b32 v1, v146, v1, v2
	s_waitcnt lgkmcnt(0)
	s_add_i32 s54, 0, 0x10000
	s_add_i32 s55, 0, 0x14000
	s_sext_i32_i8 s60, s4
	v_or_b32_e32 v156, s20, v150
	v_mov_b32_e32 v137, v131
	v_add_u32_e32 v138, v1, v147
	v_mov_b32_e32 v139, v131
	v_mov_b64_e32 v[140:141], 0x400
	v_mov_b64_e32 v[142:143], 0x3ff
	v_add_u32_e32 v157, s54, v155
	v_add_u32_e32 v158, s55, v155
	v_add_u32_e32 v159, 0, v0
	s_mov_b64 s[18:19], 0x80000
	s_mov_b32 s56, 0x80000
	s_mov_b64 s[20:21], 0x90000
	s_mov_b32 s57, 0x90000
	s_mov_b64 s[22:23], 0xa0000
	s_mov_b32 s58, 0xa0000
	s_mov_b64 s[36:37], 0xb0000
	s_mov_b32 s59, 0xb0000
	s_barrier
	s_branch .LBB0_1154

; #define PG8_STAGE(bufoff, gbase, voff) do { _Pragma("unroll") for (int _i = 0; _i < 2; ++_i) \
;         __builtin_amdgcn_global_load_lds((const unsigned*)((const char*)(gbase) + (voff)[_i]), (PG8_LAS unsigned*)(lds + (bufoff) + ldsw + _i * 8192), 16, 0, 0); } while (0)
; #define PG8_WAIT_V(n) asm volatile("s_waitcnt vmcnt(" #n ")" ::: "memory")
; #define PG8_BAR __builtin_amdgcn_s_barrier()
; template <class Epi, class Sched, bool ALIGN_EPI = false, bool SP2 = false>
; __device__ __forceinline__ void gemm_phase(PG8_LAS unsigned char* lds, const Gemm g, const Sched& S, const Epi& E) {
;     ...
;     const int aoff = lds_byte(wr * 64 + fr, fq * 8), boff = lds_byte(wc * 32 + fr, fq * 8);
;     ...
;     if constexpr (SP2) {
;         PG8_STAGE(PG8_SB(0, 0), cB, voffB); PG8_STAGE(PG8_SB(0, 1), cB + hstepB, voffB); PG8_STAGE(PG8_SA(0, 0), cA, voffA); PG8_STAGE(PG8_SA(0, 1), cA + hstepA, voffA);
;         if (wr == 1) PG8_BAR;
;         PG8_WAIT_V(2); PG8_BAR;
;         PG8_STAGE(PG8_SB(1, 0), cB + kstep, voffB); PG8_STAGE(PG8_SA(1, 0), cA + kstep, voffA); PG8_STAGE(PG8_SB(1, 1), cB + hstepB + kstep, voffB);
;         PG8_WAIT_V(6); PG8_BAR;
.LBB0_1256:
	s_lshl_b32 s8, s8, 5
	s_and_b32 s16, s8, 0x60
	s_mov_b64 s[8:9], 0x80
	s_add_i32 m0, s33, 0x18000
	v_lshl_add_u64 v[6:7], v[6:7], 0, s[8:9]
	s_lshl_b32 s11, s10, 13
	s_lshl_b32 s17, s16, 7
	global_load_lds_dwordx4 v[6:7], off
	v_lshl_add_u64 v[4:5], v[4:5], 0, s[8:9]
	s_add_i32 m0, s33, 0x1a000
	s_add_i32 s61, s33, 0x8000
	s_add_i32 s62, s33, 0xa000
	global_load_lds_dwordx4 v[4:5], off
	v_lshl_add_u64 v[0:1], v[0:1], 0, s[8:9]
	s_mov_b32 m0, s61
	s_add_u32 s14, s42, 0x10080
	global_load_lds_dwordx4 v[0:1], off
	v_lshl_add_u64 v[0:1], v[2:3], 0, s[8:9]
	s_mov_b32 m0, s62
	s_addc_u32 s15, s43, 0
	global_load_lds_dwordx4 v[0:1], off
	s_add_i32 m0, s33, 0x1c000
	v_lshl_add_u64 v[0:1], s[14:15], 0, v[132:133]
	global_load_lds_dwordx4 v[0:1], off
	v_lshl_add_u64 v[0:1], s[14:15], 0, v[128:129]
	s_add_i32 m0, s33, 0x1e000
	s_sext_i32_i8 s68, s4
	global_load_lds_dwordx4 v[0:1], off
	s_waitcnt vmcnt(8)
	s_barrier
	v_and_b32_e32 v0, 15, v162
	v_lshlrev_b32_e32 v1, 1, v8
	v_lshlrev_b32_e32 v2, 2, v162
	v_lshlrev_b32_e32 v3, 6, v162
	s_movk_i32 s4, 0x3c0
	v_lshl_or_b32 v142, s10, 6, v0
	v_lshl_or_b32 v0, v0, 6, v1
	v_and_b32_e32 v2, 32, v2
	v_and_or_b32 v1, v3, s4, v1
	s_waitcnt vmcnt(6)
	s_cmpk_lt_u32 s5, 0x100
	v_bitop3_b32 v0, v0, s11, v2 bitop3:0xde
	v_bitop3_b32 v143, s17, v1, v2 bitop3:0xf6
	s_cselect_b64 s[10:11], -1, 0
	s_add_i32 s63, 0, 0x10000
	s_add_i32 s64, 0, 0x14000
	v_or_b32_e32 v144, s16, v8
	v_mov_b64_e32 v[136:137], 0x420
	v_mov_b64_e32 v[138:139], 0x41f
	v_add_u32_e32 v145, s63, v143
	v_add_u32_e32 v146, s64, v143
	v_add_u32_e32 v147, 0, v0
	s_mov_b64 s[14:15], 0x90000
	s_mov_b32 s65, 0x90000
	s_mov_b64 s[16:17], 0xa0000
	s_mov_b32 s66, 0xa0000
	s_mov_b64 s[18:19], 0xb0000
	s_mov_b32 s67, 0xb0000
	s_barrier
	s_branch .LBB0_1259
